# MoBA own-block epilogue: the 24 partial-output loads are issued together up front and waited once instead of one load plus vmcnt(0) each
# speedup vs baseline: 1.0141x; 1.0141x over previous
; __device__ __forceinline__ unsigned cvt_pk_bf16(float lo, float hi) { f32x2_t v = {lo, hi}; bf16x2_t b = __builtin_convertvector(v, bf16x2_t); return __builtin_bit_cast(unsigned, b); }
; __device__ __forceinline__ float bf_lo(unsigned w) { return __uint_as_float(w << 16); }
; __device__ __forceinline__ float bf_hi(unsigned w) { return __uint_as_float(w & 0xffff0000u); }
; __device__ __forceinline__ float fast_exp2(float x) { return __builtin_amdgcn_exp2f(x); }
; __device__ __forceinline__ float fast_rcp(float x) { return __builtin_amdgcn_rcpf(x); }
; __device__ __forceinline__ float swap_sum(float v) { auto rr = __builtin_amdgcn_permlane32_swap(__float_as_uint(v), __float_as_uint(v), false, false); return __uint_as_float(rr[0]) + __uint_as_float(rr[1]); }
; __device__ __forceinline__ void moba_own_unit(LAS char* lds, int bh, int jblk, const bf16_t* H, const bf16_t* PO, const float* PML, bf16_t* U, int tid) {
;     ...
;     const float lt = swap_sum(l);
;     const float mown = m - slope2 * (float)(qpos - s0);
;     float M = mown;
; #pragma unroll
;     for (int s = 0; s < 3; ++s) if (s < nsel) M = fmaxf(M, mi[s]);
;     const float wown = fast_exp2(mown - M); float den = wown * lt;
; #pragma unroll
;     for (int s = 0; s < 3; ++s) { wi[s] = (s < nsel) ? wi[s] * fast_exp2(mi[s] - M) : 0.f; den += wi[s]; }
;     const float inv = fast_rcp(den);
;     bf16_t* urow = U + ((size_t)b * SEQ + qpos) * 2048 + U_MOBA + h * 64;
; #pragma unroll
;     for (int d0 = 0; d0 < 2; ++d0)
; #pragma unroll
;         for (int g = 0; g < 4; ++g) { const int d = 32 * d0 + 8 * g + 4 * hh; const f32x16& o = d0 ? o1 : o0;
;             float a0 = o[4 * g] * wown, a1 = o[4 * g + 1] * wown, a2 = o[4 * g + 2] * wown, a3 = o[4 * g + 3] * wown;
; #pragma unroll
;             for (int s = 0; s < 3; ++s) if (s < nsel) { const u32x2 pv = *(const u32x2*)(PO + (pidx + s) * 64 + d); a0 += wi[s] * bf_lo(pv.x); a1 += wi[s] * bf_hi(pv.x); a2 += wi[s] * bf_lo(pv.y); a3 += wi[s] * bf_hi(pv.y); }
;             const u32x2 z = zr.z[d0][g];
;             u32x2 w; w.x = cvt_pk_bf16(a0 * inv * bf_lo(z.x), a1 * inv * bf_hi(z.x)); w.y = cvt_pk_bf16(a2 * inv * bf_lo(z.y), a3 * inv * bf_hi(z.y));
.LBB0_725:
	v_subrev_u32_e32 v36, s24, v144
	v_cvt_f32_i32_e32 v36, v36
	v_max_f32_e32 v37, v146, v146
	v_max_f32_e32 v38, v140, v140
	s_waitcnt lgkmcnt(0)
	s_barrier
	v_fma_f32 v36, -v148, v36, v122
	v_max_f32_e32 v37, v36, v37
	v_cndmask_b32_e64 v37, v36, v37, s[40:41]
	v_max_f32_e32 v38, v37, v38
	v_cndmask_b32_e64 v37, v37, v38, s[42:43]
	v_max_f32_e32 v38, v142, v142
	v_max_f32_e32 v38, v37, v38
	v_cndmask_b32_e64 v37, v37, v38, s[44:45]
	v_sub_f32_e32 v36, v36, v37
	v_exp_f32_e32 v38, v36
	v_sub_f32_e32 v36, v146, v37
	v_exp_f32_e32 v36, v36
	v_mov_b32_e32 v35, v34
	s_nop 1
	v_permlane32_swap_b32_e32 v34, v35
	v_mul_f32_e32 v36, v147, v36
	v_mul_f32_e32 v42, v18, v38
	v_mul_f32_e32 v43, v19, v38
	v_mul_f32_e32 v40, v20, v38
	v_mul_f32_e32 v41, v21, v38
	s_and_b64 vcc, exec, s[40:41]
	s_cbranch_vccz .Lown_pf_done
	v_mad_u64_u32 v[96:97], s[4:5], v145, s10, v[102:103]
	v_mov_b32_e32 v98, v97
	v_mad_u64_u32 v[98:99], s[4:5], v123, s10, v[98:99]
	v_mov_b32_e32 v150, v96
	v_mov_b32_e32 v151, v98
	v_mad_u64_u32 v[96:97], s[4:5], v145, s10, v[104:105]
	v_mov_b32_e32 v98, v97
	v_mad_u64_u32 v[98:99], s[4:5], v123, s10, v[98:99]
	v_mov_b32_e32 v152, v96
	v_mov_b32_e32 v153, v98
	v_mad_u64_u32 v[96:97], s[4:5], v145, s10, v[106:107]
	v_mov_b32_e32 v98, v97
	v_mad_u64_u32 v[98:99], s[4:5], v123, s10, v[98:99]
	v_mov_b32_e32 v154, v96
	v_mov_b32_e32 v155, v98
	v_mad_u64_u32 v[96:97], s[4:5], v145, s10, v[108:109]
	v_mov_b32_e32 v98, v97
	v_mad_u64_u32 v[98:99], s[4:5], v123, s10, v[98:99]
	v_mov_b32_e32 v156, v96
	v_mov_b32_e32 v157, v98
	v_mad_u64_u32 v[96:97], s[4:5], v145, s10, v[110:111]
	v_mov_b32_e32 v98, v97
	v_mad_u64_u32 v[98:99], s[4:5], v123, s10, v[98:99]
	v_mov_b32_e32 v158, v96
	v_mov_b32_e32 v159, v98
	v_mad_u64_u32 v[96:97], s[4:5], v145, s10, v[112:113]
	v_mov_b32_e32 v98, v97
	v_mad_u64_u32 v[98:99], s[4:5], v123, s10, v[98:99]
	v_mov_b32_e32 v160, v96
	v_mov_b32_e32 v161, v98
	v_mad_u64_u32 v[96:97], s[4:5], v145, s10, v[114:115]
	v_mov_b32_e32 v98, v97
	v_mad_u64_u32 v[98:99], s[4:5], v123, s10, v[98:99]
	v_mov_b32_e32 v162, v96
	v_mov_b32_e32 v163, v98
	v_mad_u64_u32 v[96:97], s[4:5], v145, s10, v[116:117]
	v_mov_b32_e32 v98, v97
	v_mad_u64_u32 v[98:99], s[4:5], v123, s10, v[98:99]
	v_mov_b32_e32 v164, v96
	v_mov_b32_e32 v165, v98
	s_nop 0
	global_load_dwordx2 v[48:49], v[150:151], off
	global_load_dwordx2 v[54:55], v[152:153], off
	global_load_dwordx2 v[60:61], v[154:155], off
	global_load_dwordx2 v[66:67], v[156:157], off
	global_load_dwordx2 v[72:73], v[158:159], off
	global_load_dwordx2 v[78:79], v[160:161], off
	global_load_dwordx2 v[84:85], v[162:163], off
	global_load_dwordx2 v[90:91], v[164:165], off
	s_and_b64 vcc, exec, s[42:43]
	s_cbranch_vccz .Lown_pf_done
	global_load_dwordx2 v[50:51], v[150:151], off offset:128
	global_load_dwordx2 v[56:57], v[152:153], off offset:128
	global_load_dwordx2 v[62:63], v[154:155], off offset:128
	global_load_dwordx2 v[68:69], v[156:157], off offset:128
	global_load_dwordx2 v[74:75], v[158:159], off offset:128
	global_load_dwordx2 v[80:81], v[160:161], off offset:128
	global_load_dwordx2 v[86:87], v[162:163], off offset:128
	global_load_dwordx2 v[92:93], v[164:165], off offset:128
	s_and_b64 vcc, exec, s[44:45]
	s_cbranch_vccz .Lown_pf_done
	global_load_dwordx2 v[52:53], v[150:151], off offset:256
	global_load_dwordx2 v[58:59], v[152:153], off offset:256
	global_load_dwordx2 v[64:65], v[154:155], off offset:256
	global_load_dwordx2 v[70:71], v[156:157], off offset:256
	global_load_dwordx2 v[76:77], v[158:159], off offset:256
	global_load_dwordx2 v[82:83], v[160:161], off offset:256
	global_load_dwordx2 v[88:89], v[162:163], off offset:256
	global_load_dwordx2 v[94:95], v[164:165], off offset:256
.Lown_pf_done:
	s_and_b64 vcc, exec, s[40:41]
	s_cbranch_vccz .LBB0_727
	s_waitcnt vmcnt(0)
	v_mov_b32_e32 v18, v48
	v_mov_b32_e32 v19, v49
	v_lshlrev_b32_e32 v20, 16, v18
	v_and_b32_e32 v21, 0xffff0000, v18
	v_lshlrev_b32_e32 v18, 16, v19
	v_and_b32_e32 v19, 0xffff0000, v19
	v_fma_f32 v42, v36, v20, v42
	v_fma_f32 v43, v36, v21, v43
	v_fma_f32 v40, v36, v18, v40
	v_fma_f32 v41, v36, v19, v41
.LBB0_727:
	v_sub_f32_e32 v18, v140, v37
	v_exp_f32_e32 v18, v18
	v_cndmask_b32_e64 v19, 0, 1, s[42:43]
	v_cmp_ne_u32_e64 s[46:47], 1, v19
	s_andn2_b64 vcc, exec, s[42:43]
	v_mul_f32_e32 v18, v141, v18
	s_cbranch_vccnz .LBB0_729
	v_mov_b32_e32 v20, v50
	v_mov_b32_e32 v21, v51
	v_lshlrev_b32_e32 v44, 16, v20
	v_and_b32_e32 v45, 0xffff0000, v20
	v_lshlrev_b32_e32 v20, 16, v21
	v_and_b32_e32 v21, 0xffff0000, v21
	v_fma_f32 v42, v18, v44, v42
	v_fma_f32 v43, v18, v45, v43
	v_fma_f32 v40, v18, v20, v40
	v_fma_f32 v41, v18, v21, v41
.LBB0_729:
	v_sub_f32_e32 v19, v142, v37
	v_exp_f32_e32 v19, v19
	v_cndmask_b32_e64 v20, 0, 1, s[44:45]
	v_cmp_ne_u32_e64 s[48:49], 1, v20
	s_andn2_b64 vcc, exec, s[44:45]
	v_mul_f32_e32 v20, v143, v19
	s_cbranch_vccnz .LBB0_731
	v_mov_b32_e32 v44, v52
	v_mov_b32_e32 v45, v53
	v_lshlrev_b32_e32 v46, 16, v44
	v_and_b32_e32 v47, 0xffff0000, v44
	v_lshlrev_b32_e32 v44, 16, v45
	v_and_b32_e32 v45, 0xffff0000, v45
	v_fma_f32 v42, v20, v46, v42
	v_fma_f32 v43, v20, v47, v43
	v_fma_f32 v40, v20, v44, v40
	v_fma_f32 v41, v20, v45, v41
; __device__ __forceinline__ unsigned cvt_pk_bf16(float lo, float hi) { f32x2_t v = {lo, hi}; bf16x2_t b = __builtin_convertvector(v, bf16x2_t); return __builtin_bit_cast(unsigned, b); }
; __device__ __forceinline__ float bf_lo(unsigned w) { return __uint_as_float(w << 16); }
; __device__ __forceinline__ float bf_hi(unsigned w) { return __uint_as_float(w & 0xffff0000u); }
; __device__ __forceinline__ void moba_own_unit(LAS char* lds, int bh, int jblk, const bf16_t* H, const bf16_t* PO, const float* PML, bf16_t* U, int tid) {
;     ...
; #pragma unroll
;     for (int d0 = 0; d0 < 2; ++d0)
; #pragma unroll
;         for (int g = 0; g < 4; ++g) { const int d = 32 * d0 + 8 * g + 4 * hh; const f32x16& o = d0 ? o1 : o0;
;             float a0 = o[4 * g] * wown, a1 = o[4 * g + 1] * wown, a2 = o[4 * g + 2] * wown, a3 = o[4 * g + 3] * wown;
; #pragma unroll
;             for (int s = 0; s < 3; ++s) if (s < nsel) { const u32x2 pv = *(const u32x2*)(PO + (pidx + s) * 64 + d); a0 += wi[s] * bf_lo(pv.x); a1 += wi[s] * bf_hi(pv.x); a2 += wi[s] * bf_lo(pv.y); a3 += wi[s] * bf_hi(pv.y); }
;             const u32x2 z = zr.z[d0][g];
;             u32x2 w; w.x = cvt_pk_bf16(a0 * inv * bf_lo(z.x), a1 * inv * bf_hi(z.x)); w.y = cvt_pk_bf16(a2 * inv * bf_lo(z.y), a3 * inv * bf_hi(z.y));
;             *(u32x2*)(urow + d) = w; }
.LBB0_731:
	v_add_f32_e32 v19, v34, v35
	v_cndmask_b32_e64 v21, 0, v36, s[40:41]
	v_fmac_f32_e32 v21, v38, v19
	v_cndmask_b32_e64 v19, 0, v18, s[42:43]
	v_add_f32_e32 v19, v19, v21
	v_cndmask_b32_e64 v21, 0, v20, s[44:45]
	v_add_f32_e32 v19, v21, v19
	v_rcp_f32_e32 v34, v19
	v_lshlrev_b64 v[44:45], 12, v[138:139]
	v_lshlrev_b32_e32 v46, 16, v136
	v_and_b32_e32 v47, 0xffff0000, v136
	v_mul_f32_e32 v42, v34, v42
	v_mul_f32_e32 v43, v34, v43
	v_lshl_add_u64 v[44:45], s[0:1], 0, v[44:45]
	v_mul_f32_e32 v42, v42, v46
	v_mul_f32_e32 v43, v43, v47
	v_mul_f32_e32 v40, v34, v40
	v_mul_f32_e32 v41, v34, v41
	v_lshlrev_b32_e32 v46, 16, v137
	v_and_b32_e32 v47, 0xffff0000, v137
	v_lshl_add_u64 v[44:45], v[44:45], 0, s[30:31]
	v_mul_f32_e32 v40, v40, v46
	v_mul_f32_e32 v41, v41, v47
	v_mov_b32_e32 v119, v1
	v_cvt_pk_bf16_f32 v42, v42, v43
	v_cvt_pk_bf16_f32 v43, v40, v41
	v_lshl_add_u64 v[40:41], v[44:45], 0, v[118:119]
	v_add_co_u32_e32 v44, vcc, 0x10200000, v40
	v_mov_b32_e32 v39, v38
	s_nop 0
	v_addc_co_u32_e32 v45, vcc, 0, v41, vcc
	v_cndmask_b32_e64 v19, 0, 1, s[40:41]
	global_store_dwordx2 v[44:45], v[42:43], off offset:2048
	v_mul_f32_e32 v42, v22, v38
	v_mul_f32_e32 v43, v23, v39
	v_cmp_ne_u32_e64 s[42:43], 1, v19
	s_andn2_b64 vcc, exec, s[40:41]
	v_mul_f32_e32 v24, v24, v38
	v_mul_f32_e32 v25, v25, v39
	s_cbranch_vccnz .LBB0_733
	v_mov_b32_e32 v22, v54
	v_mov_b32_e32 v23, v55
	v_lshlrev_b32_e32 v44, 16, v22
	v_and_b32_e32 v45, 0xffff0000, v22
	v_lshlrev_b32_e32 v22, 16, v23
	v_and_b32_e32 v23, 0xffff0000, v23
	v_fma_f32 v42, v36, v44, v42
	v_fma_f32 v43, v36, v45, v43
	v_fma_f32 v24, v36, v22, v24
	v_fma_f32 v25, v36, v23, v25
.LBB0_733:
	s_and_b64 vcc, exec, s[46:47]
	s_cbranch_vccnz .LBB0_735
	v_mov_b32_e32 v22, v56
	v_mov_b32_e32 v23, v57
	v_lshlrev_b32_e32 v44, 16, v22
	v_and_b32_e32 v45, 0xffff0000, v22
	v_lshlrev_b32_e32 v22, 16, v23
	v_and_b32_e32 v23, 0xffff0000, v23
	v_fma_f32 v42, v18, v44, v42
	v_fma_f32 v43, v18, v45, v43
	v_fma_f32 v24, v18, v22, v24
	v_fma_f32 v25, v18, v23, v25
.LBB0_735:
	s_and_b64 vcc, exec, s[48:49]
	s_cbranch_vccnz .LBB0_737
	v_mov_b32_e32 v22, v58
	v_mov_b32_e32 v23, v59
	v_lshlrev_b32_e32 v44, 16, v22
	v_and_b32_e32 v45, 0xffff0000, v22
	v_lshlrev_b32_e32 v22, 16, v23
	v_and_b32_e32 v23, 0xffff0000, v23
	v_fma_f32 v42, v20, v44, v42
	v_fma_f32 v43, v20, v45, v43
	v_fma_f32 v24, v20, v22, v24
	v_fma_f32 v25, v20, v23, v25
.LBB0_737:
	v_mov_b32_e32 v35, v34
	s_mov_b64 s[4:5], 0x10200800
	v_lshl_add_u64 v[22:23], v[40:41], 0, s[4:5]
	v_mul_f32_e32 v40, v34, v42
	v_mul_f32_e32 v41, v35, v43
	v_lshlrev_b32_e32 v42, 16, v134
	v_and_b32_e32 v43, 0xffff0000, v134
	v_mul_f32_e32 v40, v40, v42
	v_mul_f32_e32 v41, v41, v43
	v_mul_f32_e32 v24, v34, v24
	v_mul_f32_e32 v25, v35, v25
	v_lshlrev_b32_e32 v42, 16, v135
	v_and_b32_e32 v43, 0xffff0000, v135
	v_mul_f32_e32 v24, v24, v42
	v_mul_f32_e32 v25, v25, v43
	v_cvt_pk_bf16_f32 v40, v40, v41
	v_cvt_pk_bf16_f32 v41, v24, v25
	v_mul_f32_e32 v26, v26, v38
	v_mul_f32_e32 v27, v27, v39
	s_and_b64 vcc, exec, s[42:43]
	v_mul_f32_e32 v24, v28, v38
	v_mul_f32_e32 v25, v29, v39
	global_store_dwordx2 v[22:23], v[40:41], off offset:16
	s_cbranch_vccnz .LBB0_739
	v_mov_b32_e32 v28, v60
	v_mov_b32_e32 v29, v61
	v_lshlrev_b32_e32 v40, 16, v28
	v_and_b32_e32 v41, 0xffff0000, v28
	v_lshlrev_b32_e32 v28, 16, v29
	v_and_b32_e32 v29, 0xffff0000, v29
	v_fma_f32 v26, v36, v40, v26
	v_fma_f32 v27, v36, v41, v27
	v_fma_f32 v24, v36, v28, v24
	v_fma_f32 v25, v36, v29, v25
.LBB0_739:
	s_and_b64 vcc, exec, s[46:47]
	s_cbranch_vccnz .LBB0_741
	v_mov_b32_e32 v28, v62
	v_mov_b32_e32 v29, v63
	v_lshlrev_b32_e32 v40, 16, v28
	v_and_b32_e32 v41, 0xffff0000, v28
	v_lshlrev_b32_e32 v28, 16, v29
	v_and_b32_e32 v29, 0xffff0000, v29
	v_fma_f32 v26, v18, v40, v26
	v_fma_f32 v27, v18, v41, v27
	v_fma_f32 v24, v18, v28, v24
	v_fma_f32 v25, v18, v29, v25
.LBB0_741:
	s_and_b64 vcc, exec, s[48:49]
	s_cbranch_vccnz .LBB0_743
	v_mov_b32_e32 v28, v64
	v_mov_b32_e32 v29, v65
	v_lshlrev_b32_e32 v40, 16, v28
	v_and_b32_e32 v41, 0xffff0000, v28
	v_lshlrev_b32_e32 v28, 16, v29
	v_and_b32_e32 v29, 0xffff0000, v29
	v_fma_f32 v26, v20, v40, v26
	v_fma_f32 v27, v20, v41, v27
	v_fma_f32 v24, v20, v28, v24
	v_fma_f32 v25, v20, v29, v25
.LBB0_743:
	v_mul_f32_e32 v26, v34, v26
	v_mul_f32_e32 v27, v35, v27
	v_lshlrev_b32_e32 v28, 16, v132
	v_and_b32_e32 v29, 0xffff0000, v132
	v_mul_f32_e32 v26, v26, v28
	v_mul_f32_e32 v27, v27, v29
	v_mul_f32_e32 v24, v34, v24
	v_mul_f32_e32 v25, v35, v25
	v_lshlrev_b32_e32 v28, 16, v133
	v_and_b32_e32 v29, 0xffff0000, v133
	v_mul_f32_e32 v24, v24, v28
	v_mul_f32_e32 v25, v25, v29
	v_cvt_pk_bf16_f32 v26, v26, v27
	v_cvt_pk_bf16_f32 v27, v24, v25
	global_store_dwordx2 v[22:23], v[26:27], off offset:32
	v_mul_f32_e32 v26, v30, v38
	v_mul_f32_e32 v27, v31, v39
	s_and_b64 vcc, exec, s[42:43]
	v_mul_f32_e32 v24, v32, v38
	v_mul_f32_e32 v25, v33, v39
	s_cbranch_vccnz .LBB0_745
	v_mov_b32_e32 v28, v66
	v_mov_b32_e32 v29, v67
	v_lshlrev_b32_e32 v30, 16, v28
	v_and_b32_e32 v31, 0xffff0000, v28
	v_lshlrev_b32_e32 v28, 16, v29
	v_and_b32_e32 v29, 0xffff0000, v29
	v_fma_f32 v26, v36, v30, v26
	v_fma_f32 v27, v36, v31, v27
	v_fma_f32 v24, v36, v28, v24
	v_fma_f32 v25, v36, v29, v25
.LBB0_745:
	s_and_b64 vcc, exec, s[46:47]
	s_cbranch_vccnz .LBB0_747
	v_mov_b32_e32 v28, v68
	v_mov_b32_e32 v29, v69
	v_lshlrev_b32_e32 v30, 16, v28
	v_and_b32_e32 v31, 0xffff0000, v28
	v_lshlrev_b32_e32 v28, 16, v29
	v_and_b32_e32 v29, 0xffff0000, v29
	v_fma_f32 v26, v18, v30, v26
	v_fma_f32 v27, v18, v31, v27
	v_fma_f32 v24, v18, v28, v24
	v_fma_f32 v25, v18, v29, v25
; __device__ __forceinline__ unsigned cvt_pk_bf16(float lo, float hi) { f32x2_t v = {lo, hi}; bf16x2_t b = __builtin_convertvector(v, bf16x2_t); return __builtin_bit_cast(unsigned, b); }
; __device__ __forceinline__ float bf_lo(unsigned w) { return __uint_as_float(w << 16); }
; __device__ __forceinline__ float bf_hi(unsigned w) { return __uint_as_float(w & 0xffff0000u); }
; __device__ __forceinline__ void moba_own_unit(LAS char* lds, int bh, int jblk, const bf16_t* H, const bf16_t* PO, const float* PML, bf16_t* U, int tid) {
;     ...
; #pragma unroll
;     for (int d0 = 0; d0 < 2; ++d0)
; #pragma unroll
;         for (int g = 0; g < 4; ++g) { const int d = 32 * d0 + 8 * g + 4 * hh; const f32x16& o = d0 ? o1 : o0;
;             float a0 = o[4 * g] * wown, a1 = o[4 * g + 1] * wown, a2 = o[4 * g + 2] * wown, a3 = o[4 * g + 3] * wown;
; #pragma unroll
;             for (int s = 0; s < 3; ++s) if (s < nsel) { const u32x2 pv = *(const u32x2*)(PO + (pidx + s) * 64 + d); a0 += wi[s] * bf_lo(pv.x); a1 += wi[s] * bf_hi(pv.x); a2 += wi[s] * bf_lo(pv.y); a3 += wi[s] * bf_hi(pv.y); }
;             const u32x2 z = zr.z[d0][g];
;             u32x2 w; w.x = cvt_pk_bf16(a0 * inv * bf_lo(z.x), a1 * inv * bf_hi(z.x)); w.y = cvt_pk_bf16(a2 * inv * bf_lo(z.y), a3 * inv * bf_hi(z.y));
;             *(u32x2*)(urow + d) = w; }
.LBB0_747:
	s_and_b64 vcc, exec, s[48:49]
	s_cbranch_vccnz .LBB0_749
	v_mov_b32_e32 v28, v70
	v_mov_b32_e32 v29, v71
	v_lshlrev_b32_e32 v30, 16, v28
	v_and_b32_e32 v31, 0xffff0000, v28
	v_lshlrev_b32_e32 v28, 16, v29
	v_and_b32_e32 v29, 0xffff0000, v29
	v_fma_f32 v26, v20, v30, v26
	v_fma_f32 v27, v20, v31, v27
	v_fma_f32 v24, v20, v28, v24
	v_fma_f32 v25, v20, v29, v25
.LBB0_749:
	v_mul_f32_e32 v26, v34, v26
	v_mul_f32_e32 v27, v35, v27
	v_lshlrev_b32_e32 v28, 16, v130
	v_and_b32_e32 v29, 0xffff0000, v130
	v_mul_f32_e32 v26, v26, v28
	v_mul_f32_e32 v27, v27, v29
	v_mul_f32_e32 v24, v34, v24
	v_mul_f32_e32 v25, v35, v25
	v_lshlrev_b32_e32 v28, 16, v131
	v_and_b32_e32 v29, 0xffff0000, v131
	v_mul_f32_e32 v24, v24, v28
	v_mul_f32_e32 v25, v25, v29
	v_cvt_pk_bf16_f32 v26, v26, v27
	v_cvt_pk_bf16_f32 v27, v24, v25
	v_mul_f32_e32 v24, v2, v38
	v_mul_f32_e32 v25, v3, v39
	s_and_b64 vcc, exec, s[42:43]
	v_mul_f32_e32 v2, v4, v38
	v_mul_f32_e32 v3, v5, v39
	global_store_dwordx2 v[22:23], v[26:27], off offset:48
	s_cbranch_vccnz .LBB0_751
	v_mov_b32_e32 v4, v72
	v_mov_b32_e32 v5, v73
	v_lshlrev_b32_e32 v26, 16, v4
	v_and_b32_e32 v27, 0xffff0000, v4
	v_lshlrev_b32_e32 v4, 16, v5
	v_and_b32_e32 v5, 0xffff0000, v5
	v_fma_f32 v24, v36, v26, v24
	v_fma_f32 v25, v36, v27, v25
	v_fma_f32 v2, v36, v4, v2
	v_fma_f32 v3, v36, v5, v3
.LBB0_751:
	s_and_b64 vcc, exec, s[46:47]
	s_cbranch_vccnz .LBB0_753
	v_mov_b32_e32 v4, v74
	v_mov_b32_e32 v5, v75
	v_lshlrev_b32_e32 v26, 16, v4
	v_and_b32_e32 v27, 0xffff0000, v4
	v_lshlrev_b32_e32 v4, 16, v5
	v_and_b32_e32 v5, 0xffff0000, v5
	v_fma_f32 v24, v18, v26, v24
	v_fma_f32 v25, v18, v27, v25
	v_fma_f32 v2, v18, v4, v2
	v_fma_f32 v3, v18, v5, v3
.LBB0_753:
	s_and_b64 vcc, exec, s[48:49]
	s_cbranch_vccnz .LBB0_755
	v_mov_b32_e32 v4, v76
	v_mov_b32_e32 v5, v77
	v_lshlrev_b32_e32 v26, 16, v4
	v_and_b32_e32 v27, 0xffff0000, v4
	v_lshlrev_b32_e32 v4, 16, v5
	v_and_b32_e32 v5, 0xffff0000, v5
	v_fma_f32 v24, v20, v26, v24
	v_fma_f32 v25, v20, v27, v25
	v_fma_f32 v2, v20, v4, v2
	v_fma_f32 v3, v20, v5, v3
.LBB0_755:
	v_mul_f32_e32 v4, v34, v24
	v_mul_f32_e32 v5, v35, v25
	v_lshlrev_b32_e32 v24, 16, v128
	v_and_b32_e32 v25, 0xffff0000, v128
	v_mul_f32_e32 v4, v4, v24
	v_mul_f32_e32 v5, v5, v25
	v_mul_f32_e32 v2, v34, v2
	v_mul_f32_e32 v3, v35, v3
	v_lshlrev_b32_e32 v24, 16, v129
	v_and_b32_e32 v25, 0xffff0000, v129
	v_mul_f32_e32 v2, v2, v24
	v_mul_f32_e32 v3, v3, v25
	v_cvt_pk_bf16_f32 v4, v4, v5
	v_cvt_pk_bf16_f32 v5, v2, v3
	global_store_dwordx2 v[22:23], v[4:5], off offset:64
	v_mul_f32_e32 v4, v6, v38
	v_mul_f32_e32 v5, v7, v39
	s_and_b64 vcc, exec, s[42:43]
	v_mul_f32_e32 v2, v8, v38
	v_mul_f32_e32 v3, v9, v39
	s_cbranch_vccnz .LBB0_757
	v_mov_b32_e32 v6, v78
	v_mov_b32_e32 v7, v79
	v_lshlrev_b32_e32 v8, 16, v6
	v_and_b32_e32 v9, 0xffff0000, v6
	v_lshlrev_b32_e32 v6, 16, v7
	v_and_b32_e32 v7, 0xffff0000, v7
	v_fma_f32 v4, v36, v8, v4
	v_fma_f32 v5, v36, v9, v5
	v_fma_f32 v2, v36, v6, v2
	v_fma_f32 v3, v36, v7, v3
.LBB0_757:
	s_and_b64 vcc, exec, s[46:47]
	s_cbranch_vccnz .LBB0_759
	v_mov_b32_e32 v6, v80
	v_mov_b32_e32 v7, v81
	v_lshlrev_b32_e32 v8, 16, v6
	v_and_b32_e32 v9, 0xffff0000, v6
	v_lshlrev_b32_e32 v6, 16, v7
	v_and_b32_e32 v7, 0xffff0000, v7
	v_fma_f32 v4, v18, v8, v4
	v_fma_f32 v5, v18, v9, v5
	v_fma_f32 v2, v18, v6, v2
	v_fma_f32 v3, v18, v7, v3
.LBB0_759:
	s_and_b64 vcc, exec, s[48:49]
	s_cbranch_vccnz .LBB0_761
	v_mov_b32_e32 v6, v82
	v_mov_b32_e32 v7, v83
	v_lshlrev_b32_e32 v8, 16, v6
	v_and_b32_e32 v9, 0xffff0000, v6
	v_lshlrev_b32_e32 v6, 16, v7
	v_and_b32_e32 v7, 0xffff0000, v7
	v_fma_f32 v4, v20, v8, v4
	v_fma_f32 v5, v20, v9, v5
	v_fma_f32 v2, v20, v6, v2
	v_fma_f32 v3, v20, v7, v3
.LBB0_761:
	v_mul_f32_e32 v4, v34, v4
	v_mul_f32_e32 v5, v35, v5
	v_lshlrev_b32_e32 v6, 16, v126
	v_and_b32_e32 v7, 0xffff0000, v126
	v_mul_f32_e32 v4, v4, v6
	v_mul_f32_e32 v5, v5, v7
	v_mul_f32_e32 v2, v34, v2
	v_mul_f32_e32 v3, v35, v3
	v_lshlrev_b32_e32 v6, 16, v127
	v_and_b32_e32 v7, 0xffff0000, v127
	v_mul_f32_e32 v2, v2, v6
	v_mul_f32_e32 v3, v3, v7
	v_cvt_pk_bf16_f32 v4, v4, v5
	v_cvt_pk_bf16_f32 v5, v2, v3
	global_store_dwordx2 v[22:23], v[4:5], off offset:80
	v_mul_f32_e32 v4, v10, v38
	v_mul_f32_e32 v5, v11, v39
	s_and_b64 vcc, exec, s[42:43]
	v_mul_f32_e32 v2, v12, v38
	v_mul_f32_e32 v3, v13, v39
	s_cbranch_vccnz .LBB0_763
	v_mov_b32_e32 v6, v84
	v_mov_b32_e32 v7, v85
	v_lshlrev_b32_e32 v8, 16, v6
	v_and_b32_e32 v9, 0xffff0000, v6
	v_lshlrev_b32_e32 v6, 16, v7
	v_and_b32_e32 v7, 0xffff0000, v7
	v_fma_f32 v4, v36, v8, v4
	v_fma_f32 v5, v36, v9, v5
	v_fma_f32 v2, v36, v6, v2
	v_fma_f32 v3, v36, v7, v3
.LBB0_763:
	s_and_b64 vcc, exec, s[46:47]
	s_cbranch_vccnz .LBB0_765
	v_mov_b32_e32 v6, v86
	v_mov_b32_e32 v7, v87
	v_lshlrev_b32_e32 v8, 16, v6
	v_and_b32_e32 v9, 0xffff0000, v6
	v_lshlrev_b32_e32 v6, 16, v7
	v_and_b32_e32 v7, 0xffff0000, v7
	v_fma_f32 v4, v18, v8, v4
	v_fma_f32 v5, v18, v9, v5
	v_fma_f32 v2, v18, v6, v2
	v_fma_f32 v3, v18, v7, v3
.LBB0_765:
	s_and_b64 vcc, exec, s[48:49]
	s_cbranch_vccnz .LBB0_767
	v_mov_b32_e32 v6, v88
	v_mov_b32_e32 v7, v89
	v_lshlrev_b32_e32 v8, 16, v6
	v_and_b32_e32 v9, 0xffff0000, v6
	v_lshlrev_b32_e32 v6, 16, v7
	v_and_b32_e32 v7, 0xffff0000, v7
	v_fma_f32 v4, v20, v8, v4
	v_fma_f32 v5, v20, v9, v5
	v_fma_f32 v2, v20, v6, v2
	v_fma_f32 v3, v20, v7, v3
.LBB0_767:
	v_mul_f32_e32 v4, v34, v4
	v_mul_f32_e32 v5, v35, v5
	v_lshlrev_b32_e32 v6, 16, v124
	v_and_b32_e32 v7, 0xffff0000, v124
	v_mul_f32_e32 v4, v4, v6
	v_mul_f32_e32 v5, v5, v7
	v_mul_f32_e32 v2, v34, v2
	v_mul_f32_e32 v3, v35, v3
	v_lshlrev_b32_e32 v6, 16, v125
	v_and_b32_e32 v7, 0xffff0000, v125
	v_mul_f32_e32 v2, v2, v6
	v_mul_f32_e32 v3, v3, v7
	v_cvt_pk_bf16_f32 v4, v4, v5
	v_cvt_pk_bf16_f32 v5, v2, v3
	global_store_dwordx2 v[22:23], v[4:5], off offset:96
	v_mul_f32_e32 v4, v14, v38
	v_mul_f32_e32 v5, v15, v39
	s_and_b64 vcc, exec, s[42:43]
	v_mul_f32_e32 v2, v16, v38
	v_mul_f32_e32 v3, v17, v39
	s_cbranch_vccnz .LBB0_769
	v_mov_b32_e32 v6, v90
	v_mov_b32_e32 v7, v91
	v_lshlrev_b32_e32 v8, 16, v6
	v_and_b32_e32 v9, 0xffff0000, v6
	v_lshlrev_b32_e32 v6, 16, v7
	v_and_b32_e32 v7, 0xffff0000, v7
	v_fma_f32 v4, v36, v8, v4
	v_fma_f32 v5, v36, v9, v5
	v_fma_f32 v2, v36, v6, v2
	v_fma_f32 v3, v36, v7, v3
.LBB0_769:
	s_and_b64 vcc, exec, s[46:47]
	s_cbranch_vccnz .LBB0_771
	v_mov_b32_e32 v6, v92
	v_mov_b32_e32 v7, v93
	v_lshlrev_b32_e32 v8, 16, v6
	v_and_b32_e32 v9, 0xffff0000, v6
	v_lshlrev_b32_e32 v6, 16, v7
	v_and_b32_e32 v7, 0xffff0000, v7
	v_fma_f32 v4, v18, v8, v4
	v_fma_f32 v5, v18, v9, v5
	v_fma_f32 v2, v18, v6, v2
	v_fma_f32 v3, v18, v7, v3
.LBB0_771:
	s_and_b64 vcc, exec, s[48:49]
	s_cbranch_vccnz .LBB0_631
	v_mov_b32_e32 v6, v94
	v_mov_b32_e32 v7, v95
	v_lshlrev_b32_e32 v8, 16, v6
	v_and_b32_e32 v9, 0xffff0000, v6
	v_lshlrev_b32_e32 v6, 16, v7
	v_and_b32_e32 v7, 0xffff0000, v7
	v_fma_f32 v4, v20, v8, v4
	v_fma_f32 v5, v20, v9, v5
	v_fma_f32 v2, v20, v6, v2
	v_fma_f32 v3, v20, v7, v3
	s_branch .LBB0_631
